# gate mini-GEMM: row blocks assigned so each workgroup reads the token rows its own XCD just streamed in the in-projection (L2 locality; any bijection is correct)
# speedup vs baseline: 1.0018x; 1.0018x over previous
;     __host__ __device__ bool next(int i, Unit& u) const {
;     ...
;         int wgid = (int)L; { const int q = nwg / NXCD, r = nwg % NXCD, xcd = wgid % NXCD, off = wgid / NXCD; wgid = (xcd < r ? xcd * (q + 1) : r * (q + 1) + (xcd - r) * q) + off; }
;         const int nig = WGM * nN, gid = wgid / nig, fm = gid * WGM, gsz = (nM - fm) < WGM ? (nM - fm) : WGM;
;         u.pm = fm + ((wgid % nig) % gsz); u.pn = (wgid % nig) / gsz; return true;
;     __device__ __forceinline__ void operator()(const f32x4 (&acc)[2][2][4][2], const Unit& u, int wr, int wc, int fr, int fq) const {
;     ...
;         } else if (wc == 0) {
; #pragma unroll
;             for (int ai = 0; ai < 2; ++ai)
; #pragma unroll
;                 for (int m = 0; m < 4; ++m) { float* gp = G + (size_t)(row0 + ai * HALF + m * 16) * 32 + 8 * fq;
;                     *(f32x4*)gp = acc[ai][0][m][0]; *(f32x4*)(gp + 4) = acc[ai][0][m][1]; }
.Lgate_loop:
	s_and_b32 s13, s12, 7
	s_lshl_b32 s13, s13, 5
	s_lshr_b32 s7, s12, 3
	s_add_u32 s13, s13, s7
	s_lshl_b32 s6, s13, 18
	s_add_u32 s6, s6, s5
	s_add_u32 s6, s6, 0x17a00000
	s_add_u32 s16, s60, s6
	s_addc_u32 s17, s61, 0
	v_mov_b32_e32 v2, 0
	v_mov_b32_e32 v3, 0
	v_mov_b32_e32 v4, 0
	v_mov_b32_e32 v5, 0
	v_mov_b32_e32 v6, 0
	v_mov_b32_e32 v7, 0
	v_mov_b32_e32 v8, 0
	v_mov_b32_e32 v9, 0
	v_mov_b32_e32 v10, 0
	v_mov_b32_e32 v11, 0
	v_mov_b32_e32 v12, 0
	v_mov_b32_e32 v13, 0
	v_mov_b32_e32 v14, 0
	v_mov_b32_e32 v15, 0
	v_mov_b32_e32 v16, 0
	v_mov_b32_e32 v17, 0
	v_mov_b32_e32 v18, 0
	v_mov_b32_e32 v19, 0
	v_mov_b32_e32 v20, 0
	v_mov_b32_e32 v21, 0
	v_mov_b32_e32 v22, 0
	v_mov_b32_e32 v23, 0
	v_mov_b32_e32 v24, 0
	v_mov_b32_e32 v25, 0
	v_mov_b32_e32 v26, 0
	v_mov_b32_e32 v27, 0
	v_mov_b32_e32 v28, 0
	v_mov_b32_e32 v29, 0
	v_mov_b32_e32 v30, 0
	v_mov_b32_e32 v31, 0
	v_mov_b32_e32 v32, 0
	v_mov_b32_e32 v33, 0
	global_load_dwordx4 v[34:37], v134, s[16:17] offset:0
	global_load_dwordx4 v[38:41], v135, s[16:17] offset:0
	global_load_dwordx4 v[42:45], v136, s[16:17] offset:0
	global_load_dwordx4 v[46:49], v137, s[16:17] offset:0
	global_load_dwordx4 v[50:53], v134, s[8:9] offset:0
	global_load_dwordx4 v[54:57], v135, s[8:9] offset:0
	global_load_dwordx4 v[58:61], v134, s[16:17] offset:64
	global_load_dwordx4 v[62:65], v135, s[16:17] offset:64
	global_load_dwordx4 v[66:69], v136, s[16:17] offset:64
	global_load_dwordx4 v[70:73], v137, s[16:17] offset:64
	global_load_dwordx4 v[74:77], v134, s[8:9] offset:64
	global_load_dwordx4 v[78:81], v135, s[8:9] offset:64
	global_load_dwordx4 v[82:85], v134, s[16:17] offset:128
	global_load_dwordx4 v[86:89], v135, s[16:17] offset:128
	global_load_dwordx4 v[90:93], v136, s[16:17] offset:128
	global_load_dwordx4 v[94:97], v137, s[16:17] offset:128
	global_load_dwordx4 v[98:101], v134, s[8:9] offset:128
	global_load_dwordx4 v[102:105], v135, s[8:9] offset:128
	global_load_dwordx4 v[106:109], v134, s[16:17] offset:192
	global_load_dwordx4 v[110:113], v135, s[16:17] offset:192
	global_load_dwordx4 v[114:117], v136, s[16:17] offset:192
	global_load_dwordx4 v[118:121], v137, s[16:17] offset:192
	global_load_dwordx4 v[122:125], v134, s[8:9] offset:192
	global_load_dwordx4 v[126:129], v135, s[8:9] offset:192
	s_waitcnt vmcnt(18)
	v_mfma_f32_16x16x32_bf16 v[2:5], v[50:53], v[34:37], v[2:5]
	v_mfma_f32_16x16x32_bf16 v[6:9], v[54:57], v[34:37], v[6:9]
	v_mfma_f32_16x16x32_bf16 v[10:13], v[50:53], v[38:41], v[10:13]
	v_mfma_f32_16x16x32_bf16 v[14:17], v[54:57], v[38:41], v[14:17]
	v_mfma_f32_16x16x32_bf16 v[18:21], v[50:53], v[42:45], v[18:21]
	v_mfma_f32_16x16x32_bf16 v[22:25], v[54:57], v[42:45], v[22:25]
	v_mfma_f32_16x16x32_bf16 v[26:29], v[50:53], v[46:49], v[26:29]
	v_mfma_f32_16x16x32_bf16 v[30:33], v[54:57], v[46:49], v[30:33]
	global_load_dwordx4 v[34:37], v134, s[16:17] offset:256
	global_load_dwordx4 v[38:41], v135, s[16:17] offset:256
	global_load_dwordx4 v[42:45], v136, s[16:17] offset:256
	global_load_dwordx4 v[46:49], v137, s[16:17] offset:256
	global_load_dwordx4 v[50:53], v134, s[8:9] offset:256
	global_load_dwordx4 v[54:57], v135, s[8:9] offset:256
	s_waitcnt vmcnt(18)
	v_mfma_f32_16x16x32_bf16 v[2:5], v[74:77], v[58:61], v[2:5]
	v_mfma_f32_16x16x32_bf16 v[6:9], v[78:81], v[58:61], v[6:9]
	v_mfma_f32_16x16x32_bf16 v[10:13], v[74:77], v[62:65], v[10:13]
	v_mfma_f32_16x16x32_bf16 v[14:17], v[78:81], v[62:65], v[14:17]
	v_mfma_f32_16x16x32_bf16 v[18:21], v[74:77], v[66:69], v[18:21]
	v_mfma_f32_16x16x32_bf16 v[22:25], v[78:81], v[66:69], v[22:25]
	v_mfma_f32_16x16x32_bf16 v[26:29], v[74:77], v[70:73], v[26:29]
	v_mfma_f32_16x16x32_bf16 v[30:33], v[78:81], v[70:73], v[30:33]
	global_load_dwordx4 v[58:61], v134, s[16:17] offset:320
	global_load_dwordx4 v[62:65], v135, s[16:17] offset:320
	global_load_dwordx4 v[66:69], v136, s[16:17] offset:320
	global_load_dwordx4 v[70:73], v137, s[16:17] offset:320
	global_load_dwordx4 v[74:77], v134, s[8:9] offset:320
	global_load_dwordx4 v[78:81], v135, s[8:9] offset:320
	s_waitcnt vmcnt(18)
	v_mfma_f32_16x16x32_bf16 v[2:5], v[98:101], v[82:85], v[2:5]
	v_mfma_f32_16x16x32_bf16 v[6:9], v[102:105], v[82:85], v[6:9]
	v_mfma_f32_16x16x32_bf16 v[10:13], v[98:101], v[86:89], v[10:13]
	v_mfma_f32_16x16x32_bf16 v[14:17], v[102:105], v[86:89], v[14:17]
	v_mfma_f32_16x16x32_bf16 v[18:21], v[98:101], v[90:93], v[18:21]
	v_mfma_f32_16x16x32_bf16 v[22:25], v[102:105], v[90:93], v[22:25]
	v_mfma_f32_16x16x32_bf16 v[26:29], v[98:101], v[94:97], v[26:29]
	v_mfma_f32_16x16x32_bf16 v[30:33], v[102:105], v[94:97], v[30:33]
	global_load_dwordx4 v[82:85], v134, s[16:17] offset:384
	global_load_dwordx4 v[86:89], v135, s[16:17] offset:384
	global_load_dwordx4 v[90:93], v136, s[16:17] offset:384
	global_load_dwordx4 v[94:97], v137, s[16:17] offset:384
	global_load_dwordx4 v[98:101], v134, s[8:9] offset:384
	global_load_dwordx4 v[102:105], v135, s[8:9] offset:384
	s_waitcnt vmcnt(18)
;     __device__ __forceinline__ void operator()(const f32x4 (&acc)[2][2][4][2], const Unit& u, int wr, int wc, int fr, int fq) const {
;     ...
;         } else if (wc == 0) {
; #pragma unroll
;             for (int ai = 0; ai < 2; ++ai)
; #pragma unroll
;                 for (int m = 0; m < 4; ++m) { float* gp = G + (size_t)(row0 + ai * HALF + m * 16) * 32 + 8 * fq;
;                     *(f32x4*)gp = acc[ai][0][m][0]; *(f32x4*)(gp + 4) = acc[ai][0][m][1]; }
	v_mfma_f32_16x16x32_bf16 v[2:5], v[122:125], v[106:109], v[2:5]
	v_mfma_f32_16x16x32_bf16 v[6:9], v[126:129], v[106:109], v[6:9]
	v_mfma_f32_16x16x32_bf16 v[10:13], v[122:125], v[110:113], v[10:13]
	v_mfma_f32_16x16x32_bf16 v[14:17], v[126:129], v[110:113], v[14:17]
	v_mfma_f32_16x16x32_bf16 v[18:21], v[122:125], v[114:117], v[18:21]
	v_mfma_f32_16x16x32_bf16 v[22:25], v[126:129], v[114:117], v[22:25]
	v_mfma_f32_16x16x32_bf16 v[26:29], v[122:125], v[118:121], v[26:29]
	v_mfma_f32_16x16x32_bf16 v[30:33], v[126:129], v[118:121], v[30:33]
	global_load_dwordx4 v[106:109], v134, s[16:17] offset:448
	global_load_dwordx4 v[110:113], v135, s[16:17] offset:448
	global_load_dwordx4 v[114:117], v136, s[16:17] offset:448
	global_load_dwordx4 v[118:121], v137, s[16:17] offset:448
	global_load_dwordx4 v[122:125], v134, s[8:9] offset:448
	global_load_dwordx4 v[126:129], v135, s[8:9] offset:448
	s_waitcnt vmcnt(18)
	v_mfma_f32_16x16x32_bf16 v[2:5], v[50:53], v[34:37], v[2:5]
	v_mfma_f32_16x16x32_bf16 v[6:9], v[54:57], v[34:37], v[6:9]
	v_mfma_f32_16x16x32_bf16 v[10:13], v[50:53], v[38:41], v[10:13]
	v_mfma_f32_16x16x32_bf16 v[14:17], v[54:57], v[38:41], v[14:17]
	v_mfma_f32_16x16x32_bf16 v[18:21], v[50:53], v[42:45], v[18:21]
	v_mfma_f32_16x16x32_bf16 v[22:25], v[54:57], v[42:45], v[22:25]
	v_mfma_f32_16x16x32_bf16 v[26:29], v[50:53], v[46:49], v[26:29]
	v_mfma_f32_16x16x32_bf16 v[30:33], v[54:57], v[46:49], v[30:33]
	s_waitcnt vmcnt(12)
	v_mfma_f32_16x16x32_bf16 v[2:5], v[74:77], v[58:61], v[2:5]
	v_mfma_f32_16x16x32_bf16 v[6:9], v[78:81], v[58:61], v[6:9]
	v_mfma_f32_16x16x32_bf16 v[10:13], v[74:77], v[62:65], v[10:13]
	v_mfma_f32_16x16x32_bf16 v[14:17], v[78:81], v[62:65], v[14:17]
	v_mfma_f32_16x16x32_bf16 v[18:21], v[74:77], v[66:69], v[18:21]
	v_mfma_f32_16x16x32_bf16 v[22:25], v[78:81], v[66:69], v[22:25]
	v_mfma_f32_16x16x32_bf16 v[26:29], v[74:77], v[70:73], v[26:29]
	v_mfma_f32_16x16x32_bf16 v[30:33], v[78:81], v[70:73], v[30:33]
	s_waitcnt vmcnt(6)
	v_mfma_f32_16x16x32_bf16 v[2:5], v[98:101], v[82:85], v[2:5]
	v_mfma_f32_16x16x32_bf16 v[6:9], v[102:105], v[82:85], v[6:9]
	v_mfma_f32_16x16x32_bf16 v[10:13], v[98:101], v[86:89], v[10:13]
	v_mfma_f32_16x16x32_bf16 v[14:17], v[102:105], v[86:89], v[14:17]
	v_mfma_f32_16x16x32_bf16 v[18:21], v[98:101], v[90:93], v[18:21]
	v_mfma_f32_16x16x32_bf16 v[22:25], v[102:105], v[90:93], v[22:25]
	v_mfma_f32_16x16x32_bf16 v[26:29], v[98:101], v[94:97], v[26:29]
	v_mfma_f32_16x16x32_bf16 v[30:33], v[102:105], v[94:97], v[30:33]
	s_waitcnt vmcnt(0)
	v_mfma_f32_16x16x32_bf16 v[2:5], v[122:125], v[106:109], v[2:5]
	v_mfma_f32_16x16x32_bf16 v[6:9], v[126:129], v[106:109], v[6:9]
	v_mfma_f32_16x16x32_bf16 v[10:13], v[122:125], v[110:113], v[10:13]
	v_mfma_f32_16x16x32_bf16 v[14:17], v[126:129], v[110:113], v[14:17]
	v_mfma_f32_16x16x32_bf16 v[18:21], v[122:125], v[114:117], v[18:21]
	v_mfma_f32_16x16x32_bf16 v[22:25], v[126:129], v[114:117], v[22:25]
	v_mfma_f32_16x16x32_bf16 v[26:29], v[122:125], v[118:121], v[26:29]
	v_mfma_f32_16x16x32_bf16 v[30:33], v[126:129], v[118:121], v[30:33]
	s_nop 7
	s_nop 7
	ds_write_b128 v139, v[2:5] offset:0
	ds_write_b128 v139, v[6:9] offset:1024
	ds_write_b128 v139, v[10:13] offset:2048
	ds_write_b128 v139, v[14:17] offset:3072
	ds_write_b128 v139, v[18:21] offset:4096
	ds_write_b128 v139, v[22:25] offset:5120
	ds_write_b128 v139, v[26:29] offset:6144
	ds_write_b128 v139, v[30:33] offset:7168
	s_waitcnt lgkmcnt(0)
	s_barrier
	ds_read_b128 v[34:37], v140 offset:0
	ds_read_b128 v[38:41], v140 offset:8192
	ds_read_b128 v[42:45], v140 offset:16384
	ds_read_b128 v[46:49], v140 offset:24576
	ds_read_b128 v[50:53], v140 offset:32768
	ds_read_b128 v[54:57], v140 offset:40960
	ds_read_b128 v[58:61], v140 offset:49152
	ds_read_b128 v[62:65], v140 offset:57344
	s_lshl_b32 s6, s13, 13
	s_lshr_b32 s7, s4, 1
	s_lshl_b32 s7, s7, 11
	s_add_u32 s6, s6, s7
	s_and_b32 s7, s4, 1
	s_lshl_b32 s7, s7, 6
	s_add_u32 s6, s6, s7
	s_add_u32 s6, s6, 0x200000
	s_add_u32 s18, s60, s6
	s_addc_u32 s19, s61, 0
	s_waitcnt lgkmcnt(6)
	v_add_f32_e32 v34, v34, v38
	v_add_f32_e32 v35, v35, v39
	v_add_f32_e32 v36, v36, v40
	v_add_f32_e32 v37, v37, v41
	s_waitcnt lgkmcnt(5)
	v_add_f32_e32 v34, v34, v42
	v_add_f32_e32 v35, v35, v43
	v_add_f32_e32 v36, v36, v44
	v_add_f32_e32 v37, v37, v45
	s_waitcnt lgkmcnt(4)
	v_add_f32_e32 v34, v34, v46
	v_add_f32_e32 v35, v35, v47
	v_add_f32_e32 v36, v36, v48
	v_add_f32_e32 v37, v37, v49
	s_waitcnt lgkmcnt(3)
	v_add_f32_e32 v34, v34, v50
	v_add_f32_e32 v35, v35, v51
	v_add_f32_e32 v36, v36, v52
	v_add_f32_e32 v37, v37, v53
	s_waitcnt lgkmcnt(2)
	v_add_f32_e32 v34, v34, v54
	v_add_f32_e32 v35, v35, v55
	v_add_f32_e32 v36, v36, v56
	v_add_f32_e32 v37, v37, v57
	s_waitcnt lgkmcnt(1)
	v_add_f32_e32 v34, v34, v58
	v_add_f32_e32 v35, v35, v59
	v_add_f32_e32 v36, v36, v60
	v_add_f32_e32 v37, v37, v61
	s_waitcnt lgkmcnt(0)
	v_add_f32_e32 v34, v34, v62
	v_add_f32_e32 v35, v35, v63
	v_add_f32_e32 v36, v36, v64
	v_add_f32_e32 v37, v37, v65
	s_nop 4
	global_store_dwordx4 v141, v[34:37], s[18:19]
	s_add_u32 s12, s12, s58
	s_cmpk_lt_u32 s12, 0x100
	s_cbranch_scc0 .Lgate_skip
	s_barrier
	s_branch .Lgate_loop
